# thr: histogram cleared by the scan threads that own the counters; separate zeroing sweep and its barrier only before the first pass
# baseline (speedup 1.0000x reference)
; DI void dsa_thr_item(const Params& p, int b, int qblk, char* smem) {
;     ...
;   for (int pass = 0; pass < 4; ++pass) {
;     for (int i = tid; i < 8192; i += 512) hist[i] = 0u;
;     __syncthreads();
.LBB0_263:
	s_mov_b64 s[52:53], 0
	v_mov_b32_e32 v0, v205
	v_mov_b32_e32 v1, v165
	s_cmp_lg_u32 s72, 0
	s_cbranch_scc1 .Lthr_nozero

; DI void dsa_thr_item(const Params& p, int b, int qblk, char* smem) {
;     ...
;     const int shift = 24 - 8 * pass;
;     const unsigned mypref = pref[lr];
;     const u16* kib = (const u16*)(p.ws + OFF_KIF) + (size_t)b * 128 * 1024 + lane * 8;
;     bf16x8 kn0, kn1;
;     {
;       const int kt0 = min(wave, qblk);
;       kn0 = ldg8(kib + (size_t)kt0 * 1024); kn1 = ldg8(kib + (size_t)kt0 * 1024 + 512);
;     }
;     for (int kt = wave; kt <= qblk; kt += 8) {
;       const bf16x8 k0 = kn0, k1 = kn1;
;       {
;         const int ktn = min(kt + 8, qblk);
;         kn0 = ldg8(kib + (size_t)ktn * 1024); kn1 = ldg8(kib + (size_t)ktn * 1024 + 512);
.Lthr_nozero:
	s_and_saveexec_b64 s[54:55], vcc
	s_cbranch_execz .LBB0_334
	global_load_dwordx4 v[36:39], v[56:57], off offset:1024
	global_load_dwordx4 v[32:35], v[56:57], off
	ds_read_b32 v94, v58 offset:32768
	ds_read_b128 v[184:187], v216 offset:33792
	ds_read_b128 v[188:191], v216 offset:33824
	ds_read_b128 v[192:195], v216 offset:33280
	ds_read_b128 v[196:199], v216 offset:33312
	ds_read_b128 v[200:203], v216 offset:33344
	ds_read_b128 v[220:223], v216 offset:33376
	ds_read_b128 v[224:227], v216 offset:33408
	ds_read_b128 v[228:231], v216 offset:33440
	ds_read_b128 v[232:235], v216 offset:33472
	ds_read_b128 v[236:239], v216 offset:33504
	ds_read_b128 v[240:243], v216 offset:33536
	ds_read_b128 v[244:247], v216 offset:33568
	ds_read_b128 v[248:251], v216 offset:33600
	s_waitcnt lgkmcnt(0)
	s_lshl_b32 s0, s72, 3
	s_sub_i32 s58, 24, s0
	s_mov_b64 s[60:61], 0
	v_mov_b32_e32 v96, v167
	s_branch .LBB0_268

; DI void dsa_thr_item(const Params& p, int b, int qblk, char* smem) {
;     ...
;     for (int i = tid; i < 8192; i += 512) hist[i] = 0u;
;     ...
;     __syncthreads();
; #pragma unroll 1
;     for (int qq = 0; qq < 4; ++qq) {
;       const int q = wave * 4 + qq;
;       const int rk = rank[q];
;       int c[4];
; #pragma unroll
;       for (int j = 0; j < 4; ++j) c[j] = (int)hist[(255 - 4 * lane - j) * 32 + q];
;       int s = c[0] + c[1] + c[2] + c[3];
;       int P = wave_incl_scan(s, lane);
;       int excl = P - s;
;       if (P >= rk && excl < rk) {
;         int cum = excl; int bin = 0; int nr = 1; bool found = false;
; #pragma unroll
;         for (int j = 0; j < 4; ++j) {
;           if (!found && cum + c[j] >= rk) { bin = 255 - 4 * lane - j; nr = rk - cum; found = true; }
;           if (!found) cum += c[j];
;         }
;         pref[q] = (pref[q] << 8) | (unsigned)bin;
;         rank[q] = nr;
;       }
;     }
.LBB0_334:
	s_or_b64 exec, exec, s[54:55]
	s_mov_b32 s58, 0
	s_waitcnt lgkmcnt(0)
	s_barrier
	v_readfirstlane_b32 s58, v167
	v_and_b32_e32 v28, 31, v177
	v_lshlrev_b32_e32 v28, 2, v28
	v_lshrrev_b32_e32 v29, 5, v177
	v_lshl_add_u32 v29, v167, 1, v29
	v_lshlrev_b32_e32 v27, 4, v29
	v_sub_u32_e32 v27, 0xff, v27
	v_lshlrev_b32_e32 v19, 11, v29
	v_sub_u32_e32 v19, 0x7800, v19
	v_add_u32_e32 v19, v19, v28
	ds_read_b32 v0, v19 offset:1920
	ds_read_b32 v1, v19 offset:1792
	ds_read_b32 v2, v19 offset:1664
	ds_read_b32 v3, v19 offset:1536
	ds_read_b32 v4, v19 offset:1408
	ds_read_b32 v5, v19 offset:1280
	ds_read_b32 v6, v19 offset:1152
	ds_read_b32 v7, v19 offset:1024
	ds_read_b32 v8, v19 offset:896
	ds_read_b32 v9, v19 offset:768
	ds_read_b32 v10, v19 offset:640
	ds_read_b32 v11, v19 offset:512
	ds_read_b32 v12, v19 offset:384
	ds_read_b32 v13, v19 offset:256
	ds_read_b32 v14, v19 offset:128
	ds_read_b32 v15, v19 offset:0
	v_add_u32_e32 v21, 0x8000, v28
	ds_read_b32 v22, v21 offset:128
	ds_read_b32 v23, v21
	s_mov_b32 s60, 0
	s_mov_b32 s61, -1
	s_mov_b32 s62, -1
	s_mov_b32 s63, 0
	s_waitcnt lgkmcnt(0)
	v_mov_b32_e32 v38, 0
	ds_write_b32 v19, v38 offset:1920
	ds_write_b32 v19, v38 offset:1792
	ds_write_b32 v19, v38 offset:1664
	ds_write_b32 v19, v38 offset:1536
	ds_write_b32 v19, v38 offset:1408
	ds_write_b32 v19, v38 offset:1280
	ds_write_b32 v19, v38 offset:1152
	ds_write_b32 v19, v38 offset:1024
	ds_write_b32 v19, v38 offset:896
	ds_write_b32 v19, v38 offset:768
	ds_write_b32 v19, v38 offset:640
	ds_write_b32 v19, v38 offset:512
	ds_write_b32 v19, v38 offset:384
	ds_write_b32 v19, v38 offset:256
	ds_write_b32 v19, v38 offset:128
	ds_write_b32 v19, v38 offset:0
	v_add3_u32 v16, v0, v1, v2
	v_add3_u32 v17, v3, v4, v5
	v_add3_u32 v18, v6, v7, v8
	v_add3_u32 v29, v9, v10, v11
	v_add3_u32 v16, v16, v17, v18
	v_add3_u32 v29, v29, v12, v13
	v_add3_u32 v16, v16, v14, v15
	v_add_u32_e32 v16, v16, v29
	v_mov_b32_e32 v17, v16
	v_mov_b32_e32 v18, v16
	s_nop 1
	v_permlane32_swap_b32_e32 v17, v18
	v_lshlrev_b32_e32 v20, 7, v167
	v_add_u32_e32 v20, v20, v28
	v_add_u32_e32 v20, 0x10000, v20
	v_add_u32_e32 v29, v16, v18
	s_and_saveexec_b64 s[64:65], s[62:63]
	ds_write_b32 v20, v29
	s_mov_b64 exec, s[64:65]
	v_add_u32_e32 v21, 0x10000, v28
	s_waitcnt lgkmcnt(0)
	s_barrier
	ds_read_b32 v30, v21 offset:0
	ds_read_b32 v31, v21 offset:128
	ds_read_b32 v32, v21 offset:256
	ds_read_b32 v33, v21 offset:384
	ds_read_b32 v34, v21 offset:512
	ds_read_b32 v35, v21 offset:640
	ds_read_b32 v36, v21 offset:768
	v_cndmask_b32_e64 v24, 0, v17, s[60:61]
	s_waitcnt lgkmcnt(0)
	s_cmp_gt_u32 s58, 0
	s_cselect_b32 s74, -1, 0
	v_and_b32_e32 v30, s74, v30
	v_add_u32_e32 v24, v24, v30
	s_cmp_gt_u32 s58, 1
	s_cselect_b32 s74, -1, 0
	v_and_b32_e32 v31, s74, v31
	v_add_u32_e32 v24, v24, v31
	s_cmp_gt_u32 s58, 2
	s_cselect_b32 s74, -1, 0
	v_and_b32_e32 v32, s74, v32
	v_add_u32_e32 v24, v24, v32
	s_cmp_gt_u32 s58, 3
	s_cselect_b32 s74, -1, 0
	v_and_b32_e32 v33, s74, v33
	v_add_u32_e32 v24, v24, v33
	s_cmp_gt_u32 s58, 4
	s_cselect_b32 s74, -1, 0
	v_and_b32_e32 v34, s74, v34
	v_add_u32_e32 v24, v24, v34
	s_cmp_gt_u32 s58, 5
	s_cselect_b32 s74, -1, 0
	v_and_b32_e32 v35, s74, v35
	v_add_u32_e32 v24, v24, v35
	s_cmp_gt_u32 s58, 6
	s_cselect_b32 s74, -1, 0
	v_and_b32_e32 v36, s74, v36
	v_add_u32_e32 v24, v24, v36
	v_mov_b32_e32 v25, 0
	v_mov_b32_e32 v26, v24
	v_add_u32_e32 v0, v24, v0
	v_add_u32_e32 v1, v0, v1
	v_add_u32_e32 v2, v1, v2
	v_add_u32_e32 v3, v2, v3
	v_add_u32_e32 v4, v3, v4
	v_add_u32_e32 v5, v4, v5
	v_add_u32_e32 v6, v5, v6
	v_add_u32_e32 v7, v6, v7
	v_add_u32_e32 v8, v7, v8
	v_add_u32_e32 v9, v8, v9
	v_add_u32_e32 v10, v9, v10
	v_add_u32_e32 v11, v10, v11
	v_add_u32_e32 v12, v11, v12
	v_add_u32_e32 v13, v12, v13
	v_add_u32_e32 v14, v13, v14
	v_add_u32_e32 v15, v14, v15
	v_cmp_gt_i32_e64 s[0:1], v22, v0
	v_cmp_gt_i32_e64 s[6:7], v22, v1
	v_cmp_gt_i32_e64 s[8:9], v22, v2
	v_cmp_gt_i32_e64 s[10:11], v22, v3
	v_addc_co_u32_e64 v25, s[12:13], v25, 0, s[0:1]
	v_cndmask_b32_e64 v26, v26, v0, s[0:1]
	v_addc_co_u32_e64 v25, s[12:13], v25, 0, s[6:7]
	v_cndmask_b32_e64 v26, v26, v1, s[6:7]
	v_addc_co_u32_e64 v25, s[12:13], v25, 0, s[8:9]
	v_cndmask_b32_e64 v26, v26, v2, s[8:9]
	v_addc_co_u32_e64 v25, s[12:13], v25, 0, s[10:11]
	v_cndmask_b32_e64 v26, v26, v3, s[10:11]
	v_cmp_gt_i32_e64 s[0:1], v22, v4
	v_cmp_gt_i32_e64 s[6:7], v22, v5
	v_cmp_gt_i32_e64 s[8:9], v22, v6
	v_cmp_gt_i32_e64 s[10:11], v22, v7
	v_addc_co_u32_e64 v25, s[12:13], v25, 0, s[0:1]
	v_cndmask_b32_e64 v26, v26, v4, s[0:1]
	v_addc_co_u32_e64 v25, s[12:13], v25, 0, s[6:7]
	v_cndmask_b32_e64 v26, v26, v5, s[6:7]
	v_addc_co_u32_e64 v25, s[12:13], v25, 0, s[8:9]
	v_cndmask_b32_e64 v26, v26, v6, s[8:9]
	v_addc_co_u32_e64 v25, s[12:13], v25, 0, s[10:11]
	v_cndmask_b32_e64 v26, v26, v7, s[10:11]
	v_cmp_gt_i32_e64 s[0:1], v22, v8
	v_cmp_gt_i32_e64 s[6:7], v22, v9
	v_cmp_gt_i32_e64 s[8:9], v22, v10
	v_cmp_gt_i32_e64 s[10:11], v22, v11
	v_addc_co_u32_e64 v25, s[12:13], v25, 0, s[0:1]
	v_cndmask_b32_e64 v26, v26, v8, s[0:1]
	v_addc_co_u32_e64 v25, s[12:13], v25, 0, s[6:7]
	v_cndmask_b32_e64 v26, v26, v9, s[6:7]
	v_addc_co_u32_e64 v25, s[12:13], v25, 0, s[8:9]
	v_cndmask_b32_e64 v26, v26, v10, s[8:9]
	v_addc_co_u32_e64 v25, s[12:13], v25, 0, s[10:11]
	v_cndmask_b32_e64 v26, v26, v11, s[10:11]
	v_cmp_gt_i32_e64 s[0:1], v22, v12
	v_cmp_gt_i32_e64 s[6:7], v22, v13
	v_cmp_gt_i32_e64 s[8:9], v22, v14
	v_cmp_gt_i32_e64 s[10:11], v22, v15
	v_addc_co_u32_e64 v25, s[12:13], v25, 0, s[0:1]
	v_cndmask_b32_e64 v26, v26, v12, s[0:1]
	v_addc_co_u32_e64 v25, s[12:13], v25, 0, s[6:7]
	v_cndmask_b32_e64 v26, v26, v13, s[6:7]
	v_addc_co_u32_e64 v25, s[12:13], v25, 0, s[8:9]
	v_cndmask_b32_e64 v26, v26, v14, s[8:9]
	v_addc_co_u32_e64 v25, s[12:13], v25, 0, s[10:11]
	v_cndmask_b32_e64 v26, v26, v15, s[10:11]
	v_cmp_gt_i32_e64 s[0:1], v22, v24
	v_cmp_ge_i32_e64 s[6:7], v15, v22
	v_sub_u32_e32 v27, v27, v25
	v_sub_u32_e32 v26, v22, v26
	v_lshl_or_b32 v23, v23, 8, v27
	v_add_u32_e32 v21, 0x8000, v28
	s_and_b64 s[0:1], s[0:1], s[6:7]
	s_and_saveexec_b64 s[64:65], s[0:1]
	ds_write2_b32 v21, v23, v26 offset1:32
	s_mov_b64 exec, s[64:65]
	s_branch .LBB0_262
